# sum-check attention with interleaved DMA, without the static wave priority
# baseline (speedup 1.0000x reference)
; #define LAS __attribute__((address_space(3)))
; __device__ __forceinline__ void attn_unit2(LAS unsigned char* lds, const bf16_t* __restrict__ Q, const bf16_t* __restrict__ KN, const bf16_t* __restrict__ KPE, ...
;     ...
;     const int pi = (r32 & 0x13) | ((r32 & 4) << 1) | ((r32 & 8) >> 1);
;     const int ka_off = pi * KROW + hi * 16, va_off = KBUF + r32 * VROW + hi * 16;
;     constexpr int SLOT = KBUF + VBUF;
;     const char* dsrc[3]; unsigned dmul[3]; int dlds[3];
; #pragma unroll
;     for (int r = 0; r < 3; ++r) {
;         const int ii = wid + 8 * r;
;         if (ii < 13) {
;             const int p = 64 * ii + lane, row = p / 13, cc = p % 13;
;             if (cc >= 8 && cc < 12) { dsrc[r] = (const char*)(KPE + (size_t)row * 32 + 8 * (cc - 8)); dmul[r] = 64u; }
;             else { dsrc[r] = (const char*)(KN + (size_t)row * 512 + h * 64 + 8 * (cc == 12 ? 0 : cc)); dmul[r] = 1024u; }
;             dlds[r] = 1024 * ii;
;         } else {
;             const int p = 64 * (ii - 13) + lane, d = p / 9, cc = p % 9;
;             dsrc[r] = (const char*)(VT + (size_t)(h * 64 + (d < 64 ? d : 63)) * MT + 8 * (cc == 8 ? 0 : cc)); dmul[r] = 2u;
;             dlds[r] = KBUF + 1024 * (ii - 13);
;         }
;     }
;     ...
;     DMAT(0, 0);
;     DMAT(1, SLOT);
;     __syncthreads();
;     int sc = 0, sn = SLOT, snn = 2 * SLOT;
;     f32x16 oa0 = {}, oa1 = {}, ob0 = {}, ob1 = {};
;     float ma = -1.0e30f, mb = -1.0e30f, la = 0.f, lb = 0.f;
;     for (int t = 0; t < ntiles; ++t) {
;         __builtin_amdgcn_sched_barrier(0);
;         f32x16 sa0 = {}, sa1 = {}, sb0 = {}, sb1 = {};
;         const LAS unsigned char* ka = lds + sc + ka_off;
; #pragma unroll
;         for (int ds = 0; ds < 6; ++ds) {
;             const bf16x8 k0 = *(const LAS bf16x8*)(ka + ds * 32);
;             const bf16x8 k1 = *(const LAS bf16x8*)(ka + 32 * KROW + ds * 32);
;             sa0 = __builtin_amdgcn_mfma_f32_32x32x16_bf16(k0, qa[ds], sa0, 0, 0, 0);
;             sa1 = __builtin_amdgcn_mfma_f32_32x32x16_bf16(k1, qa[ds], sa1, 0, 0, 0);
;             sb0 = __builtin_amdgcn_mfma_f32_32x32x16_bf16(k0, qb[ds], sb0, 0, 0, 0);
;             sb1 = __builtin_amdgcn_mfma_f32_32x32x16_bf16(k1, qb[ds], sb1, 0, 0, 0);
;         }
;         __builtin_amdgcn_sched_barrier(0);
;         if (t + 2 < ntiles) DMAT(t + 2, snn);
;         u32x4 pa[4], pb[4];
.LBB0_354:
	v_and_b32_e32 v0, 19, v3
	v_lshlrev_b32_e32 v1, 1, v3
	v_lshrrev_b32_e32 v3, 1, v3
	v_and_b32_e32 v1, 8, v1
	v_and_b32_e32 v3, 4, v3
	v_or3_b32 v0, v0, v1, v3
	v_mov_b32_e32 v16, v129
	v_mov_b32_e32 v17, v129
	v_mov_b32_e32 v30, v129
	v_mov_b32_e32 v31, v129
	v_mul_u32_u24_e32 v183, 0xd0, v0
	v_mul_u32_u24_e32 v187, 0x90, v2
	v_mov_b32_e32 v18, v129
	v_mov_b32_e32 v19, v129
	v_mov_b32_e32 v20, v129
	v_mov_b32_e32 v21, v129
	v_mov_b32_e32 v22, v129
	v_mov_b32_e32 v23, v129
	v_mov_b32_e32 v24, v129
	v_mov_b32_e32 v25, v129
	v_mov_b32_e32 v26, v129
	v_mov_b32_e32 v27, v129
	v_mov_b32_e32 v28, v129
	v_mov_b32_e32 v29, v129
	v_mov_b64_e32 v[62:63], v[30:31]
	v_mov_b64_e32 v[46:47], v[30:31]
	v_mov_b64_e32 v[0:1], v[16:17]
	s_add_i32 s10, s14, 0x4080
	s_add_i32 s11, s24, 0xffffff80
	s_mov_b32 s24, 0
	v_mov_b32_e32 v191, 0
	v_mov_b32_e32 v194, 0xf149f2ca
	s_mov_b32 s25, 0xb000
	s_movk_i32 s26, 0x5800
	s_mov_b32 s14, 0
	v_mov_b64_e32 v[60:61], v[28:29]
	v_mov_b64_e32 v[58:59], v[26:27]
	v_mov_b64_e32 v[56:57], v[24:25]
	v_mov_b64_e32 v[54:55], v[22:23]
	v_mov_b64_e32 v[52:53], v[20:21]
	v_mov_b64_e32 v[50:51], v[18:19]
	v_mov_b64_e32 v[48:49], v[16:17]
	v_mov_b64_e32 v[44:45], v[28:29]
	v_mov_b64_e32 v[42:43], v[26:27]
	v_mov_b64_e32 v[40:41], v[24:25]
	v_mov_b64_e32 v[38:39], v[22:23]
	v_mov_b64_e32 v[36:37], v[20:21]
	v_mov_b64_e32 v[34:35], v[18:19]
	v_mov_b64_e32 v[32:33], v[16:17]
	v_mov_b64_e32 v[2:3], v[18:19]
	v_mov_b64_e32 v[4:5], v[20:21]
	v_mov_b64_e32 v[6:7], v[22:23]
	v_mov_b64_e32 v[8:9], v[24:25]
	v_mov_b64_e32 v[10:11], v[26:27]
	v_mov_b64_e32 v[12:13], v[28:29]
	v_mov_b64_e32 v[14:15], v[30:31]
	v_mov_b32_e32 v195, 0xf149f2ca
	v_mov_b32_e32 v193, 0
	s_mov_b32 s27, 0
	s_waitcnt vmcnt(0) lgkmcnt(0)
	s_barrier
	s_mov_b32 s34, s14
	v_mov_b32_e32 v96, 0
	v_mov_b32_e32 v97, 0
	v_mov_b32_e32 v98, 0
	v_mov_b32_e32 v99, 0
	v_mov_b32_e32 v100, 0
	v_mov_b32_e32 v101, 0
	v_mov_b32_e32 v102, 0
	v_mov_b32_e32 v103, 0
	v_mov_b32_e32 v112, 0
	v_mov_b32_e32 v113, 0
	v_mov_b32_e32 v114, 0
	v_mov_b32_e32 v115, 0
	v_mov_b32_e32 v116, 0
	v_mov_b32_e32 v117, 0
	v_mov_b32_e32 v118, 0
	v_mov_b32_e32 v119, 0
	v_sub_u32_e32 v228, 1, v192
	v_mul_u32_u24_e32 v228, 0xffff, v228
	v_and_b32_e32 v240, 0x3f80, v228
	v_mov_b32_e32 v241, 0
	v_mov_b32_e32 v242, 0
	v_mov_b32_e32 v243, 0
	v_mov_b32_e32 v245, 0
	v_mov_b32_e32 v246, 0
	v_mov_b32_e32 v247, 0
	v_mov_b32_e32 v249, 0
	v_mov_b32_e32 v250, 0
	v_mov_b32_e32 v251, 0
	v_add3_u32 v224, s34, v183, v128
	ds_read_b128 v[212:215], v224 offset:0
	ds_read_b128 v[216:219], v224 offset:32
	ds_read_b128 v[220:223], v224 offset:64
	s_waitcnt lgkmcnt(2)
	v_mfma_f32_32x32x16_bf16 v[64:79], v[212:215], v[130:133], 0
	v_mfma_f32_32x32x16_bf16 v[80:95], v[212:215], v[138:141], 0
	ds_read_b128 v[212:215], v224 offset:96
	s_waitcnt lgkmcnt(2)
	v_mfma_f32_32x32x16_bf16 v[64:79], v[216:219], v[134:137], v[64:79]
	v_mfma_f32_32x32x16_bf16 v[80:95], v[216:219], v[142:145], v[80:95]
	ds_read_b128 v[216:219], v224 offset:128
	s_waitcnt lgkmcnt(2)
	v_mfma_f32_32x32x16_bf16 v[64:79], v[220:223], v[146:149], v[64:79]
	v_mfma_f32_32x32x16_bf16 v[80:95], v[220:223], v[154:157], v[80:95]
	ds_read_b128 v[220:223], v224 offset:160
	s_waitcnt lgkmcnt(2)
	v_mfma_f32_32x32x16_bf16 v[64:79], v[212:215], v[150:153], v[64:79]
	v_mfma_f32_32x32x16_bf16 v[80:95], v[212:215], v[158:161], v[80:95]
	s_waitcnt lgkmcnt(1)
	v_mfma_f32_32x32x16_bf16 v[64:79], v[216:219], v[162:165], v[64:79]
	v_mfma_f32_32x32x16_bf16 v[80:95], v[216:219], v[170:173], v[80:95]
	s_waitcnt lgkmcnt(0)
	v_mfma_f32_32x32x16_bf16 v[64:79], v[220:223], v[166:169], v[64:79]
	v_mfma_f32_32x32x16_bf16 v[80:95], v[220:223], v[174:177], v[80:95]
	s_nop 15
	s_nop 3
	v_max3_f32 v226, v64, v65, v66
	v_max3_f32 v227, v67, v68, v69
	v_max3_f32 v226, v226, v70, v71
	v_max3_f32 v227, v227, v72, v73
	v_max3_f32 v226, v226, v74, v75
	v_max3_f32 v227, v227, v76, v77
	v_max3_f32 v226, v226, v78, v79
	v_max_f32_e32 v226, v226, v227
	v_mov_b32_e32 v227, v226
	s_nop 1
	v_permlane32_swap_b32_e32 v226, v227
	v_max_f32_e32 v226, v226, v227
	v_cvt_pk_bf16_f32 v227, v226, v226
	v_and_b32_e32 v194, 0xffff0000, v227
	v_xor_b32_e32 v227, 0x80000000, v194
	v_lshrrev_b32_e32 v227, 16, v227
	v_and_b32_e32 v244, v228, v227
	v_max3_f32 v236, v80, v81, v82
	v_max3_f32 v237, v83, v84, v85
	v_max3_f32 v236, v236, v86, v87
	v_max3_f32 v237, v237, v88, v89
	v_max3_f32 v236, v236, v90, v91
	v_max3_f32 v237, v237, v92, v93
	v_max3_f32 v236, v236, v94, v95
	v_max_f32_e32 v236, v236, v237
	v_mov_b32_e32 v237, v236
	s_nop 1
	v_permlane32_swap_b32_e32 v236, v237
	v_max_f32_e32 v236, v236, v237
	v_cvt_pk_bf16_f32 v237, v236, v236
	v_and_b32_e32 v195, 0xffff0000, v237
	v_xor_b32_e32 v237, 0x80000000, v195
	v_lshrrev_b32_e32 v237, 16, v237
	v_and_b32_e32 v248, v228, v237
	s_nop 3
	v_mfma_f32_32x32x16_bf16 v[64:79], v[240:243], v[244:247], v[64:79]
	v_mfma_f32_32x32x16_bf16 v[80:95], v[240:243], v[248:251], v[80:95]
	v_add3_u32 v225, s34, v187, v128
	ds_read_b128 v[196:199], v225 offset:13376
	ds_read_b128 v[200:203], v225 offset:17984
	ds_read_b128 v[204:207], v225 offset:13408
	ds_read_b128 v[208:211], v225 offset:18016
	s_nop 7
	s_nop 3
	s_nop 0
